# seam barriers: the per-CU L1 invalidate is issued on arrival (overlapping the wait for the release) instead of after the release
# speedup vs baseline: 1.0166x; 1.0166x over previous
.LBB0_102:
	s_or_b64 exec, exec, s[14:15]
	v_cvt_f32_u32_e32 v4, v2
	s_waitcnt vmcnt(0)
	v_readfirstlane_b32 s3, v3
	v_sub_u32_e32 v3, 0, v2
	v_rcp_iflag_f32_e32 v4, v4
	v_add_u32_e32 v5, s3, v1
	v_mul_f32_e32 v4, 0x4f7ffffe, v4
	v_cvt_u32_f32_e32 v4, v4
	v_mul_lo_u32 v1, v3, v4
	v_mul_hi_u32 v1, v4, v1
	v_add_u32_e32 v1, v4, v1
	v_mul_hi_u32 v1, v5, v1
	v_mul_lo_u32 v3, v1, v2
	v_sub_u32_e32 v3, v5, v3
	v_add_u32_e32 v4, 1, v1
	v_cmp_ge_u32_e32 vcc, v3, v2
	s_nop 1
	v_cndmask_b32_e32 v1, v1, v4, vcc
	v_sub_u32_e32 v4, v3, v2
	v_cndmask_b32_e32 v3, v3, v4, vcc
	v_add_u32_e32 v4, 1, v1
	v_cmp_ge_u32_e32 vcc, v3, v2
	v_add_u32_e32 v3, 1, v5
	s_nop 0
	v_cndmask_b32_e32 v1, v1, v4, vcc
	v_mul_lo_u32 v4, v2, v1
	v_add_u32_e32 v2, v4, v2
	v_cmp_ne_u32_e32 vcc, v3, v2
	s_and_saveexec_b64 s[12:13], vcc
	s_xor_b64 s[12:13], exec, s[12:13]
	s_cbranch_execz .LBB0_116
	s_waitcnt lgkmcnt(0)
	buffer_inv sc1
	v_mov_b32_e32 v0, 0x2000
	global_load_dword v0, v0, s[10:11] offset:1024 sc1
	s_add_u32 s16, s10, 0x2400
	s_addc_u32 s17, s11, 0
	s_waitcnt vmcnt(0)
	v_cmp_eq_u32_e32 vcc, v0, v1
	s_and_saveexec_b64 s[14:15], vcc
	s_cbranch_execz .LBB0_115
	s_mov_b32 s3, 1
	s_mov_b64 s[20:21], 0
	v_mov_b32_e32 v0, 0
	s_branch .LBB0_106

.LBB0_115:
	s_or_b64 exec, exec, s[14:15]
	s_waitcnt vmcnt(0)
	s_waitcnt vmcnt(0)

.LBB0_119:
	s_or_b64 exec, exec, s[14:15]
	buffer_inv sc1
	v_cvt_f32_u32_e32 v3, v0
	s_waitcnt vmcnt(1)
	v_readfirstlane_b32 s3, v2
	s_add_u32 s14, s8, 0x3500
	s_addc_u32 s15, s9, 0
	v_rcp_iflag_f32_e32 v3, v3
	v_add_u32_e32 v1, s3, v1
	v_add_u32_e32 v4, 1, v1
	s_mov_b64 s[16:17], -1
	v_mul_f32_e32 v2, 0x4f7ffffe, v3
	v_cvt_u32_f32_e32 v2, v2
	v_sub_u32_e32 v3, 0, v0
	v_mul_lo_u32 v3, v3, v2
	v_mul_hi_u32 v3, v2, v3
	v_add_u32_e32 v2, v2, v3
	v_mul_hi_u32 v2, v1, v2
	v_mul_lo_u32 v3, v2, v0
	v_sub_u32_e32 v1, v1, v3
	v_add_u32_e32 v5, 1, v2
	v_cmp_ge_u32_e32 vcc, v1, v0
	v_sub_u32_e32 v3, v1, v0
	s_nop 0
	v_cndmask_b32_e32 v2, v2, v5, vcc
	v_cndmask_b32_e32 v1, v1, v3, vcc
	v_add_u32_e32 v3, 1, v2
	v_cmp_ge_u32_e32 vcc, v1, v0
	s_nop 1
	v_cndmask_b32_e32 v2, v2, v3, vcc
	v_mul_lo_u32 v1, v0, v2
	v_add_u32_e32 v0, v1, v0
	v_cmp_ne_u32_e32 vcc, v4, v0
	v_mov_b64_e32 v[0:1], s[14:15]
	s_and_saveexec_b64 s[12:13], vcc
	s_cbranch_execz .LBB0_131
	v_mov_b32_e32 v0, 0
	global_load_dword v1, v0, s[14:15] sc1
	s_mov_b64 s[22:23], 0
	s_waitcnt vmcnt(0)
	v_cmp_eq_u32_e32 vcc, v1, v2
	s_and_saveexec_b64 s[20:21], vcc
	s_cbranch_execz .LBB0_130
	s_add_u32 s16, s8, 0x200
	s_addc_u32 s17, s9, 0
	s_mov_b32 s3, 1
	s_mov_b64 s[8:9], 0
	s_branch .LBB0_123

.LBB0_133:
	s_or_b64 exec, exec, s[8:9]
	s_mov_b64 s[8:9], exec
	v_mbcnt_lo_u32_b32 v0, s8, 0
	v_mbcnt_hi_u32_b32 v0, s9, v0
	v_cmp_eq_u32_e32 vcc, 0, v0
	s_waitcnt vmcnt(0)
	s_and_saveexec_b64 s[12:13], vcc
	s_cbranch_execz .LBB0_135
	s_bcnt1_i32_b64 s3, s[8:9]
	v_mov_b32_e32 v0, 0x2000
	v_mov_b32_e32 v1, s3
	global_atomic_add v0, v1, s[10:11] offset:1024

.LBB0_202:
	s_or_b64 exec, exec, s[16:17]
	v_cvt_f32_u32_e32 v4, v2
	s_waitcnt vmcnt(0)
	v_readfirstlane_b32 s3, v3
	v_sub_u32_e32 v3, 0, v2
	v_rcp_iflag_f32_e32 v4, v4
	v_add_u32_e32 v5, s3, v1
	v_mul_f32_e32 v4, 0x4f7ffffe, v4
	v_cvt_u32_f32_e32 v4, v4
	v_mul_lo_u32 v1, v3, v4
	v_mul_hi_u32 v1, v4, v1
	v_add_u32_e32 v1, v4, v1
	v_mul_hi_u32 v1, v5, v1
	v_mul_lo_u32 v3, v1, v2
	v_sub_u32_e32 v3, v5, v3
	v_add_u32_e32 v4, 1, v1
	v_cmp_ge_u32_e32 vcc, v3, v2
	s_nop 1
	v_cndmask_b32_e32 v1, v1, v4, vcc
	v_sub_u32_e32 v4, v3, v2
	v_cndmask_b32_e32 v3, v3, v4, vcc
	v_add_u32_e32 v4, 1, v1
	v_cmp_ge_u32_e32 vcc, v3, v2
	v_add_u32_e32 v3, 1, v5
	s_nop 0
	v_cndmask_b32_e32 v1, v1, v4, vcc
	v_mul_lo_u32 v4, v2, v1
	v_add_u32_e32 v2, v4, v2
	v_cmp_ne_u32_e32 vcc, v3, v2
	s_and_saveexec_b64 s[14:15], vcc
	s_xor_b64 s[14:15], exec, s[14:15]
	s_cbranch_execz .LBB0_216
	s_waitcnt lgkmcnt(0)
	buffer_inv sc1
	v_mov_b32_e32 v0, 0x2000
	global_load_dword v0, v0, s[12:13] offset:1024 sc1
	s_add_u32 s20, s12, 0x2400
	s_addc_u32 s21, s13, 0
	s_waitcnt vmcnt(0)
	v_cmp_eq_u32_e32 vcc, v0, v1
	s_and_saveexec_b64 s[16:17], vcc
	s_cbranch_execz .LBB0_215
	s_mov_b32 s3, 1
	s_mov_b64 s[22:23], 0
	v_mov_b32_e32 v0, 0
	s_branch .LBB0_206

.LBB0_215:
	s_or_b64 exec, exec, s[16:17]
	s_waitcnt vmcnt(0)
	s_waitcnt vmcnt(0)

.LBB0_219:
	s_or_b64 exec, exec, s[16:17]
	buffer_inv sc1
	v_cvt_f32_u32_e32 v3, v0
	s_waitcnt vmcnt(1)
	v_readfirstlane_b32 s3, v2
	s_add_u32 s16, s10, 0x3500
	s_addc_u32 s17, s11, 0
	v_rcp_iflag_f32_e32 v3, v3
	v_add_u32_e32 v1, s3, v1
	v_add_u32_e32 v4, 1, v1
	s_mov_b64 s[20:21], -1
	v_mul_f32_e32 v2, 0x4f7ffffe, v3
	v_cvt_u32_f32_e32 v2, v2
	v_sub_u32_e32 v3, 0, v0
	v_mul_lo_u32 v3, v3, v2
	v_mul_hi_u32 v3, v2, v3
	v_add_u32_e32 v2, v2, v3
	v_mul_hi_u32 v2, v1, v2
	v_mul_lo_u32 v3, v2, v0
	v_sub_u32_e32 v1, v1, v3
	v_add_u32_e32 v5, 1, v2
	v_cmp_ge_u32_e32 vcc, v1, v0
	v_sub_u32_e32 v3, v1, v0
	s_nop 0
	v_cndmask_b32_e32 v2, v2, v5, vcc
	v_cndmask_b32_e32 v1, v1, v3, vcc
	v_add_u32_e32 v3, 1, v2
	v_cmp_ge_u32_e32 vcc, v1, v0
	s_nop 1
	v_cndmask_b32_e32 v2, v2, v3, vcc
	v_mul_lo_u32 v1, v0, v2
	v_add_u32_e32 v0, v1, v0
	v_cmp_ne_u32_e32 vcc, v4, v0
	v_mov_b64_e32 v[0:1], s[16:17]
	s_and_saveexec_b64 s[14:15], vcc
	s_cbranch_execz .LBB0_231
	v_mov_b32_e32 v0, 0
	global_load_dword v1, v0, s[16:17] sc1
	s_mov_b64 s[26:27], 0
	s_waitcnt vmcnt(0)
	v_cmp_eq_u32_e32 vcc, v1, v2
	s_and_saveexec_b64 s[22:23], vcc
	s_cbranch_execz .LBB0_230
	s_add_u32 s20, s10, 0x200
	s_addc_u32 s21, s11, 0
	s_mov_b32 s3, 1
	s_mov_b64 s[10:11], 0
	s_branch .LBB0_223

.LBB0_233:
	s_or_b64 exec, exec, s[10:11]
	s_mov_b64 s[10:11], exec
	v_mbcnt_lo_u32_b32 v0, s10, 0
	v_mbcnt_hi_u32_b32 v0, s11, v0
	v_cmp_eq_u32_e32 vcc, 0, v0
	s_waitcnt vmcnt(0)
	s_and_saveexec_b64 s[14:15], vcc
	s_cbranch_execz .LBB0_235
	s_bcnt1_i32_b64 s3, s[10:11]
	v_mov_b32_e32 v0, 0x2000
	v_mov_b32_e32 v1, s3
	global_atomic_add v0, v1, s[12:13] offset:1024

.LBB0_553:
	s_or_b64 exec, exec, s[20:21]
	v_cvt_f32_u32_e32 v4, v2
	s_waitcnt vmcnt(0)
	v_readfirstlane_b32 s3, v3
	v_sub_u32_e32 v3, 0, v2
	v_rcp_iflag_f32_e32 v4, v4
	v_add_u32_e32 v5, s3, v1
	v_mul_f32_e32 v4, 0x4f7ffffe, v4
	v_cvt_u32_f32_e32 v4, v4
	v_mul_lo_u32 v1, v3, v4
	v_mul_hi_u32 v1, v4, v1
	v_add_u32_e32 v1, v4, v1
	v_mul_hi_u32 v1, v5, v1
	v_mul_lo_u32 v3, v1, v2
	v_sub_u32_e32 v3, v5, v3
	v_add_u32_e32 v4, 1, v1
	v_cmp_ge_u32_e32 vcc, v3, v2
	s_nop 1
	v_cndmask_b32_e32 v1, v1, v4, vcc
	v_sub_u32_e32 v4, v3, v2
	v_cndmask_b32_e32 v3, v3, v4, vcc
	v_add_u32_e32 v4, 1, v1
	v_cmp_ge_u32_e32 vcc, v3, v2
	v_add_u32_e32 v3, 1, v5
	s_nop 0
	v_cndmask_b32_e32 v1, v1, v4, vcc
	v_mul_lo_u32 v4, v2, v1
	v_add_u32_e32 v2, v4, v2
	v_cmp_ne_u32_e32 vcc, v3, v2
	s_and_saveexec_b64 s[16:17], vcc
	s_xor_b64 s[16:17], exec, s[16:17]
	s_cbranch_execz .LBB0_567
	s_waitcnt lgkmcnt(0)
	buffer_inv sc1
	v_mov_b32_e32 v0, 0x2000
	global_load_dword v0, v0, s[14:15] offset:1024 sc1
	s_add_u32 s22, s14, 0x2400
	s_addc_u32 s23, s15, 0
	s_waitcnt vmcnt(0)
	v_cmp_eq_u32_e32 vcc, v0, v1
	s_and_saveexec_b64 s[20:21], vcc
	s_cbranch_execz .LBB0_566
	s_mov_b32 s3, 1
	s_mov_b64 s[24:25], 0
	v_mov_b32_e32 v0, 0
	s_branch .LBB0_557

.LBB0_566:
	s_or_b64 exec, exec, s[20:21]
	s_waitcnt vmcnt(0)
	s_waitcnt vmcnt(0)

.LBB0_570:
	s_or_b64 exec, exec, s[20:21]
	buffer_inv sc1
	v_cvt_f32_u32_e32 v3, v0
	s_waitcnt vmcnt(1)
	v_readfirstlane_b32 s3, v2
	s_add_u32 s20, s12, 0x3500
	s_addc_u32 s21, s13, 0
	v_rcp_iflag_f32_e32 v3, v3
	v_add_u32_e32 v1, s3, v1
	v_add_u32_e32 v4, 1, v1
	s_mov_b64 s[22:23], -1
	v_mul_f32_e32 v2, 0x4f7ffffe, v3
	v_cvt_u32_f32_e32 v2, v2
	v_sub_u32_e32 v3, 0, v0
	v_mul_lo_u32 v3, v3, v2
	v_mul_hi_u32 v3, v2, v3
	v_add_u32_e32 v2, v2, v3
	v_mul_hi_u32 v2, v1, v2
	v_mul_lo_u32 v3, v2, v0
	v_sub_u32_e32 v1, v1, v3
	v_add_u32_e32 v5, 1, v2
	v_cmp_ge_u32_e32 vcc, v1, v0
	v_sub_u32_e32 v3, v1, v0
	s_nop 0
	v_cndmask_b32_e32 v2, v2, v5, vcc
	v_cndmask_b32_e32 v1, v1, v3, vcc
	v_add_u32_e32 v3, 1, v2
	v_cmp_ge_u32_e32 vcc, v1, v0
	s_nop 1
	v_cndmask_b32_e32 v2, v2, v3, vcc
	v_mul_lo_u32 v1, v0, v2
	v_add_u32_e32 v0, v1, v0
	v_cmp_ne_u32_e32 vcc, v4, v0
	v_mov_b64_e32 v[0:1], s[20:21]
	s_and_saveexec_b64 s[16:17], vcc
	s_cbranch_execz .LBB0_582
	v_mov_b32_e32 v0, 0
	global_load_dword v1, v0, s[20:21] sc1
	s_mov_b64 s[26:27], 0
	s_waitcnt vmcnt(0)
	v_cmp_eq_u32_e32 vcc, v1, v2
	s_and_saveexec_b64 s[24:25], vcc
	s_cbranch_execz .LBB0_581
	s_add_u32 s22, s12, 0x200
	s_addc_u32 s23, s13, 0
	s_mov_b32 s3, 1
	s_mov_b64 s[12:13], 0
	s_branch .LBB0_574

.LBB0_584:
	s_or_b64 exec, exec, s[12:13]
	s_mov_b64 s[12:13], exec
	v_mbcnt_lo_u32_b32 v0, s12, 0
	v_mbcnt_hi_u32_b32 v0, s13, v0
	v_cmp_eq_u32_e32 vcc, 0, v0
	s_waitcnt vmcnt(0)
	s_and_saveexec_b64 s[16:17], vcc
	s_cbranch_execz .LBB0_586
	s_bcnt1_i32_b64 s3, s[12:13]
	v_mov_b32_e32 v0, 0x2000
	v_mov_b32_e32 v1, s3
	global_atomic_add v0, v1, s[14:15] offset:1024

.LBB0_975:
	s_or_b64 exec, exec, s[16:17]
	buffer_inv sc1
	v_cvt_f32_u32_e32 v3, v0
	s_waitcnt vmcnt(1)
	v_readfirstlane_b32 s3, v2
	s_add_u32 s16, s10, 0x3500
	s_addc_u32 s17, s11, 0
	v_rcp_iflag_f32_e32 v3, v3
	v_add_u32_e32 v1, s3, v1
	v_add_u32_e32 v4, 1, v1
	s_mov_b64 s[20:21], -1
	v_mul_f32_e32 v2, 0x4f7ffffe, v3
	v_cvt_u32_f32_e32 v2, v2
	v_sub_u32_e32 v3, 0, v0
	v_mul_lo_u32 v3, v3, v2
	v_mul_hi_u32 v3, v2, v3
	v_add_u32_e32 v2, v2, v3
	v_mul_hi_u32 v2, v1, v2
	v_mul_lo_u32 v3, v2, v0
	v_sub_u32_e32 v1, v1, v3
	v_add_u32_e32 v5, 1, v2
	v_cmp_ge_u32_e32 vcc, v1, v0
	v_sub_u32_e32 v3, v1, v0
	s_nop 0
	v_cndmask_b32_e32 v2, v2, v5, vcc
	v_cndmask_b32_e32 v1, v1, v3, vcc
	v_add_u32_e32 v3, 1, v2
	v_cmp_ge_u32_e32 vcc, v1, v0
	s_nop 1
	v_cndmask_b32_e32 v2, v2, v3, vcc
	v_mul_lo_u32 v1, v0, v2
	v_add_u32_e32 v0, v1, v0
	v_cmp_ne_u32_e32 vcc, v4, v0
	v_mov_b64_e32 v[0:1], s[16:17]
	s_and_saveexec_b64 s[14:15], vcc
	s_cbranch_execz .LBB0_987
	v_mov_b32_e32 v0, 0
	global_load_dword v1, v0, s[16:17] sc1
	s_mov_b64 s[24:25], 0
	s_waitcnt vmcnt(0)
	v_cmp_eq_u32_e32 vcc, v1, v2
	s_and_saveexec_b64 s[22:23], vcc
	s_cbranch_execz .LBB0_986
	s_add_u32 s20, s10, 0x200
	s_addc_u32 s21, s11, 0
	s_mov_b32 s3, 1
	s_mov_b64 s[10:11], 0
	s_branch .LBB0_979

.LBB0_1224:
	s_or_b64 exec, exec, s[12:13]
	v_cvt_f32_u32_e32 v4, v2
	s_waitcnt vmcnt(0)
	v_readfirstlane_b32 s3, v3
	v_sub_u32_e32 v3, 0, v2
	v_rcp_iflag_f32_e32 v4, v4
	v_add_u32_e32 v5, s3, v1
	v_mul_f32_e32 v4, 0x4f7ffffe, v4
	v_cvt_u32_f32_e32 v4, v4
	v_mul_lo_u32 v1, v3, v4
	v_mul_hi_u32 v1, v4, v1
	v_add_u32_e32 v1, v4, v1
	v_mul_hi_u32 v1, v5, v1
	v_mul_lo_u32 v3, v1, v2
	v_sub_u32_e32 v3, v5, v3
	v_add_u32_e32 v4, 1, v1
	v_cmp_ge_u32_e32 vcc, v3, v2
	s_nop 1
	v_cndmask_b32_e32 v1, v1, v4, vcc
	v_sub_u32_e32 v4, v3, v2
	v_cndmask_b32_e32 v3, v3, v4, vcc
	v_add_u32_e32 v4, 1, v1
	v_cmp_ge_u32_e32 vcc, v3, v2
	v_add_u32_e32 v3, 1, v5
	s_nop 0
	v_cndmask_b32_e32 v1, v1, v4, vcc
	v_mul_lo_u32 v4, v2, v1
	v_add_u32_e32 v2, v4, v2
	v_cmp_ne_u32_e32 vcc, v3, v2
	s_and_saveexec_b64 s[10:11], vcc
	s_xor_b64 s[10:11], exec, s[10:11]
	s_cbranch_execz .LBB0_1238
	s_waitcnt lgkmcnt(0)
	buffer_inv sc1
	v_mov_b32_e32 v0, 0x2000
	global_load_dword v0, v0, s[8:9] offset:1024 sc1
	s_add_u32 s14, s8, 0x2400
	s_addc_u32 s15, s9, 0
	s_waitcnt vmcnt(0)
	v_cmp_eq_u32_e32 vcc, v0, v1
	s_and_saveexec_b64 s[12:13], vcc
	s_cbranch_execz .LBB0_1237
	s_mov_b32 s3, 1
	s_mov_b64 s[16:17], 0
	v_mov_b32_e32 v0, 0
	s_branch .LBB0_1228

.LBB0_1237:
	s_or_b64 exec, exec, s[12:13]
	s_waitcnt vmcnt(0)
	s_waitcnt vmcnt(0)

.LBB0_1241:
	s_or_b64 exec, exec, s[12:13]
	buffer_inv sc1
	v_cvt_f32_u32_e32 v3, v0
	s_waitcnt vmcnt(1)
	v_readfirstlane_b32 s3, v2
	s_add_u32 s12, s6, 0x3500
	s_addc_u32 s13, s7, 0
	v_rcp_iflag_f32_e32 v3, v3
	v_add_u32_e32 v1, s3, v1
	v_add_u32_e32 v4, 1, v1
	s_mov_b64 s[14:15], -1
	v_mul_f32_e32 v2, 0x4f7ffffe, v3
	v_cvt_u32_f32_e32 v2, v2
	v_sub_u32_e32 v3, 0, v0
	v_mul_lo_u32 v3, v3, v2
	v_mul_hi_u32 v3, v2, v3
	v_add_u32_e32 v2, v2, v3
	v_mul_hi_u32 v2, v1, v2
	v_mul_lo_u32 v3, v2, v0
	v_sub_u32_e32 v1, v1, v3
	v_add_u32_e32 v5, 1, v2
	v_cmp_ge_u32_e32 vcc, v1, v0
	v_sub_u32_e32 v3, v1, v0
	s_nop 0
	v_cndmask_b32_e32 v2, v2, v5, vcc
	v_cndmask_b32_e32 v1, v1, v3, vcc
	v_add_u32_e32 v3, 1, v2
	v_cmp_ge_u32_e32 vcc, v1, v0
	s_nop 1
	v_cndmask_b32_e32 v2, v2, v3, vcc
	v_mul_lo_u32 v1, v0, v2
	v_add_u32_e32 v0, v1, v0
	v_cmp_ne_u32_e32 vcc, v4, v0
	v_mov_b64_e32 v[0:1], s[12:13]
	s_and_saveexec_b64 s[10:11], vcc
	s_cbranch_execz .LBB0_1253
	v_mov_b32_e32 v0, 0
	global_load_dword v1, v0, s[12:13] sc1
	s_mov_b64 s[18:19], 0
	s_waitcnt vmcnt(0)
	v_cmp_eq_u32_e32 vcc, v1, v2
	s_and_saveexec_b64 s[16:17], vcc
	s_cbranch_execz .LBB0_1252
	s_add_u32 s14, s6, 0x200
	s_addc_u32 s15, s7, 0
	s_mov_b32 s3, 1
	s_mov_b64 s[6:7], 0
	s_branch .LBB0_1245

.LBB0_1255:
	s_or_b64 exec, exec, s[6:7]
	s_mov_b64 s[6:7], exec
	v_mbcnt_lo_u32_b32 v0, s6, 0
	v_mbcnt_hi_u32_b32 v0, s7, v0
	v_cmp_eq_u32_e32 vcc, 0, v0
	s_waitcnt vmcnt(0)
	s_and_saveexec_b64 s[10:11], vcc
	s_cbranch_execz .LBB0_1257
	s_bcnt1_i32_b64 s3, s[6:7]
	v_mov_b32_e32 v0, 0x2000
	v_mov_b32_e32 v1, s3
	global_atomic_add v0, v1, s[8:9] offset:1024
